# final rmsnorm: next rows' loads interleaved into the store stream
# baseline (speedup 1.0000x reference)
; __device__ __forceinline__ float bflo(unsigned w) { return __uint_as_float(w << 16); }
; __device__ __forceinline__ float bfhi(unsigned w) { return __uint_as_float(w & 0xffff0000u); }
; __device__ __forceinline__ void phase_final_norm(const bf16_t* Hb, const unsigned long long* ssq, const float* g, float* out, int gw, int ngw, int lane, float scale) {
;     for (int m = gw; m < MTOK; m += ngw) { const float rstd = scale / sqrtf((float)ssq[m] * (1.0f / 16777216.0f) * (1.0f / DM) + EPS);
;         const u32x4* xr = (const u32x4*)(Hb + (size_t)m * DM) + lane; f32x4* o = (f32x4*)(out + (size_t)m * DM); const f32x4* gr = (const f32x4*)g;
; #pragma unroll
;         for (int j = 0; j < 8; ++j) { const u32x4 r = xr[64 * j]; const int c4 = 2 * (64 * j + lane);
;             const f32x4 g0 = gr[c4], g1 = gr[c4 + 1];
;             o[c4] = (f32x4){bflo(r.x) * rstd * g0.x, bfhi(r.x) * rstd * g0.y, bflo(r.y) * rstd * g0.z, bfhi(r.y) * rstd * g0.w};
;             o[c4 + 1] = (f32x4){bflo(r.z) * rstd * g1.x, bfhi(r.z) * rstd * g1.y, bflo(r.w) * rstd * g1.z, bfhi(r.w) * rstd * g1.w}; } }
.Lfn_entry:
	v_lshlrev_b32_e32 v2, 4, v164
	v_lshlrev_b32_e32 v3, 5, v164
	v_mov_b32_e32 v232, 0
	s_add_u32 s20, s54, 0x1000
	s_addc_u32 s21, s55, 0
	s_add_u32 s22, s54, 0x2000
	s_addc_u32 s23, s55, 0
	s_add_u32 s24, s54, 0x3000
	s_addc_u32 s25, s55, 0
	global_load_dwordx4 v[8:11], v3, s[54:55] offset:0
	global_load_dwordx4 v[12:15], v3, s[54:55] offset:16
	global_load_dwordx4 v[16:19], v3, s[54:55] offset:2048
	global_load_dwordx4 v[20:23], v3, s[54:55] offset:2064
	global_load_dwordx4 v[24:27], v3, s[20:21] offset:0
	global_load_dwordx4 v[28:31], v3, s[20:21] offset:16
	global_load_dwordx4 v[32:35], v3, s[20:21] offset:2048
	global_load_dwordx4 v[36:39], v3, s[20:21] offset:2064
	global_load_dwordx4 v[40:43], v3, s[22:23] offset:0
	global_load_dwordx4 v[44:47], v3, s[22:23] offset:16
	global_load_dwordx4 v[48:51], v3, s[22:23] offset:2048
	global_load_dwordx4 v[52:55], v3, s[22:23] offset:2064
	global_load_dwordx4 v[56:59], v3, s[24:25] offset:0
	global_load_dwordx4 v[60:63], v3, s[24:25] offset:16
	global_load_dwordx4 v[64:67], v3, s[24:25] offset:2048
	global_load_dwordx4 v[68:71], v3, s[24:25] offset:2064
	s_add_u32 s4, s58, 0xb0000
	s_addc_u32 s5, s59, 0
	s_add_u32 s6, s58, 0x2f800000
	s_addc_u32 s7, s59, 0
	s_mul_i32 s26, s74, 0
	s_add_i32 s26, s26, s52
	s_lshl_b32 s27, s26, 3
	s_add_u32 s8, s4, s27
	s_addc_u32 s9, s5, 0
	global_load_dwordx2 v[200:201], v232, s[8:9]
	s_lshl_b32 s27, s26, 13
	s_add_u32 s8, s6, s27
	s_addc_u32 s9, s7, 0
	s_add_u32 s10, s8, 0x1000
	s_addc_u32 s11, s9, 0
	global_load_dwordx4 v[72:75], v2, s[8:9] offset:0
	global_load_dwordx4 v[76:79], v2, s[8:9] offset:1024
	global_load_dwordx4 v[80:83], v2, s[8:9] offset:2048
	global_load_dwordx4 v[84:87], v2, s[8:9] offset:3072
	global_load_dwordx4 v[88:91], v2, s[10:11] offset:0
	global_load_dwordx4 v[92:95], v2, s[10:11] offset:1024
	global_load_dwordx4 v[96:99], v2, s[10:11] offset:2048
	global_load_dwordx4 v[100:103], v2, s[10:11] offset:3072
	s_mul_i32 s26, s74, 1
	s_add_i32 s26, s26, s52
	s_lshl_b32 s27, s26, 3
	s_add_u32 s8, s4, s27
	s_addc_u32 s9, s5, 0
	global_load_dwordx2 v[202:203], v232, s[8:9]
	s_lshl_b32 s27, s26, 13
	s_add_u32 s8, s6, s27
	s_addc_u32 s9, s7, 0
	s_add_u32 s10, s8, 0x1000
	s_addc_u32 s11, s9, 0
	global_load_dwordx4 v[104:107], v2, s[8:9] offset:0
	global_load_dwordx4 v[108:111], v2, s[8:9] offset:1024
	global_load_dwordx4 v[112:115], v2, s[8:9] offset:2048
	global_load_dwordx4 v[116:119], v2, s[8:9] offset:3072
	global_load_dwordx4 v[120:123], v2, s[10:11] offset:0
	global_load_dwordx4 v[124:127], v2, s[10:11] offset:1024
	global_load_dwordx4 v[128:131], v2, s[10:11] offset:2048
	global_load_dwordx4 v[132:135], v2, s[10:11] offset:3072
	v_mov_b32_e32 v233, 0x358637bd
	v_mov_b32_e32 v234, 0x260
	s_mov_b32 s28, 0xf800000
	s_mul_i32 s26, s74, 0
	s_add_i32 s26, s26, s52
	s_lshl_b32 s27, s26, 14
	s_add_u32 s12, s56, s27
	s_addc_u32 s13, s57, 0
	s_add_u32 s14, s12, 0x1000
	s_addc_u32 s15, s13, 0
	s_add_u32 s16, s14, 0x1000
	s_addc_u32 s17, s15, 0
	s_add_u32 s18, s16, 0x1000
	s_addc_u32 s19, s17, 0
	s_waitcnt vmcnt(9)
	v_ffbh_u32_e32 v208, v201
	v_min_u32_e32 v208, 32, v208
	v_lshlrev_b64 v[200:201], v208, v[200:201]
	v_min_u32_e32 v200, 1, v200
	v_or_b32_e32 v200, v201, v200
	v_cvt_f32_u32_e32 v200, v200
	v_sub_u32_e32 v208, 32, v208
	v_ldexp_f32 v208, v200, v208
	v_mul_f32_e32 v208, 0x33800000, v208
	v_fmamk_f32 v208, v208, 0x39800000, v233
	v_mul_f32_e32 v209, 0x4f800000, v208
	v_cmp_gt_f32_e32 vcc, s28, v208
	s_nop 1
	v_cndmask_b32_e32 v208, v208, v209, vcc
	v_sqrt_f32_e32 v209, v208
	s_nop 1
	v_add_u32_e32 v210, -1, v209
	v_add_u32_e32 v211, 1, v209
	v_fma_f32 v212, -v210, v209, v208
	v_fma_f32 v213, -v211, v209, v208
	v_cmp_ge_f32_e64 s[0:1], 0, v212
	s_nop 1
	v_cndmask_b32_e64 v209, v209, v210, s[0:1]
	v_cmp_lt_f32_e64 s[0:1], 0, v213
	s_nop 1
	v_cndmask_b32_e64 v209, v209, v211, s[0:1]
	v_mul_f32_e32 v210, 0x37800000, v209
	v_cndmask_b32_e32 v209, v209, v210, vcc
	v_cmp_class_f32_e32 vcc, v208, v234
	s_nop 1
	v_cndmask_b32_e32 v208, v209, v208, vcc
	v_div_scale_f32 v209, s[0:1], v208, v208, 1.0
	v_rcp_f32_e32 v211, v209
	v_div_scale_f32 v210, vcc, 1.0, v208, 1.0
	s_nop 0
	v_fma_f32 v212, -v209, v211, 1.0
	v_fmac_f32_e32 v211, v212, v211
	v_mul_f32_e32 v212, v210, v211
	v_fma_f32 v213, -v209, v212, v210
	v_fmac_f32_e32 v212, v213, v211
	v_fma_f32 v209, -v209, v212, v210
	s_nop 1
	v_div_fmas_f32 v209, v209, v211, v212
	v_div_fixup_f32 v214, v209, v208, 1.0
	v_mov_b32_e32 v215, v214
	v_lshlrev_b32_e32 v216, 16, v72
	v_and_b32_e32 v217, 0xffff0000, v72
	v_lshlrev_b32_e32 v218, 16, v73
	v_and_b32_e32 v219, 0xffff0000, v73
	v_lshlrev_b32_e32 v220, 16, v74
	v_and_b32_e32 v221, 0xffff0000, v74
	v_lshlrev_b32_e32 v222, 16, v75
	v_and_b32_e32 v223, 0xffff0000, v75
	v_pk_mul_f32 v[216:217], v[214:215], v[216:217]
	v_pk_mul_f32 v[218:219], v[214:215], v[218:219]
	v_pk_mul_f32 v[220:221], v[214:215], v[220:221]
	v_pk_mul_f32 v[222:223], v[214:215], v[222:223]
	v_pk_mul_f32 v[216:217], v[8:9], v[216:217]
	v_pk_mul_f32 v[218:219], v[10:11], v[218:219]
	v_pk_mul_f32 v[220:221], v[12:13], v[220:221]
	v_pk_mul_f32 v[222:223], v[14:15], v[222:223]
	global_store_dwordx4 v3, v[216:219], s[12:13] offset:0
	global_store_dwordx4 v3, v[220:223], s[12:13] offset:16
	s_mul_i32 s29, s74, 2
	s_add_i32 s29, s29, s52
	s_lshl_b32 s27, s29, 3
	s_add_u32 s8, s4, s27
	s_addc_u32 s9, s5, 0
	global_load_dwordx2 v[204:205], v232, s[8:9]
	s_lshl_b32 s27, s29, 13
	s_add_u32 s8, s6, s27
	s_addc_u32 s9, s7, 0
	s_add_u32 s10, s8, 0x1000
	s_addc_u32 s11, s9, 0
	global_load_dwordx4 v[136:139], v2, s[8:9] offset:0
	v_lshlrev_b32_e32 v224, 16, v76
	v_and_b32_e32 v225, 0xffff0000, v76
; __device__ __forceinline__ float bflo(unsigned w) { return __uint_as_float(w << 16); }
; __device__ __forceinline__ float bfhi(unsigned w) { return __uint_as_float(w & 0xffff0000u); }
; __device__ __forceinline__ void phase_final_norm(const bf16_t* Hb, const unsigned long long* ssq, const float* g, float* out, int gw, int ngw, int lane, float scale) {
;     for (int m = gw; m < MTOK; m += ngw) { const float rstd = scale / sqrtf((float)ssq[m] * (1.0f / 16777216.0f) * (1.0f / DM) + EPS);
;         const u32x4* xr = (const u32x4*)(Hb + (size_t)m * DM) + lane; f32x4* o = (f32x4*)(out + (size_t)m * DM); const f32x4* gr = (const f32x4*)g;
; #pragma unroll
;         for (int j = 0; j < 8; ++j) { const u32x4 r = xr[64 * j]; const int c4 = 2 * (64 * j + lane);
;             const f32x4 g0 = gr[c4], g1 = gr[c4 + 1];
;             o[c4] = (f32x4){bflo(r.x) * rstd * g0.x, bfhi(r.x) * rstd * g0.y, bflo(r.y) * rstd * g0.z, bfhi(r.y) * rstd * g0.w};
;             o[c4 + 1] = (f32x4){bflo(r.z) * rstd * g1.x, bfhi(r.z) * rstd * g1.y, bflo(r.w) * rstd * g1.z, bfhi(r.w) * rstd * g1.w}; } }
	v_lshlrev_b32_e32 v226, 16, v77
	v_and_b32_e32 v227, 0xffff0000, v77
	v_lshlrev_b32_e32 v228, 16, v78
	v_and_b32_e32 v229, 0xffff0000, v78
	v_lshlrev_b32_e32 v230, 16, v79
	v_and_b32_e32 v231, 0xffff0000, v79
	v_pk_mul_f32 v[224:225], v[214:215], v[224:225]
	v_pk_mul_f32 v[226:227], v[214:215], v[226:227]
	v_pk_mul_f32 v[228:229], v[214:215], v[228:229]
	v_pk_mul_f32 v[230:231], v[214:215], v[230:231]
	v_pk_mul_f32 v[224:225], v[16:17], v[224:225]
	v_pk_mul_f32 v[226:227], v[18:19], v[226:227]
	v_pk_mul_f32 v[228:229], v[20:21], v[228:229]
	v_pk_mul_f32 v[230:231], v[22:23], v[230:231]
	global_store_dwordx4 v3, v[224:227], s[12:13] offset:2048
	global_store_dwordx4 v3, v[228:231], s[12:13] offset:2064
	global_load_dwordx4 v[140:143], v2, s[8:9] offset:1024
	v_lshlrev_b32_e32 v216, 16, v80
	v_and_b32_e32 v217, 0xffff0000, v80
	v_lshlrev_b32_e32 v218, 16, v81
	v_and_b32_e32 v219, 0xffff0000, v81
	v_lshlrev_b32_e32 v220, 16, v82
	v_and_b32_e32 v221, 0xffff0000, v82
	v_lshlrev_b32_e32 v222, 16, v83
	v_and_b32_e32 v223, 0xffff0000, v83
	v_pk_mul_f32 v[216:217], v[214:215], v[216:217]
	v_pk_mul_f32 v[218:219], v[214:215], v[218:219]
	v_pk_mul_f32 v[220:221], v[214:215], v[220:221]
	v_pk_mul_f32 v[222:223], v[214:215], v[222:223]
	v_pk_mul_f32 v[216:217], v[24:25], v[216:217]
	v_pk_mul_f32 v[218:219], v[26:27], v[218:219]
	v_pk_mul_f32 v[220:221], v[28:29], v[220:221]
	v_pk_mul_f32 v[222:223], v[30:31], v[222:223]
	global_store_dwordx4 v3, v[216:219], s[14:15] offset:0
	global_store_dwordx4 v3, v[220:223], s[14:15] offset:16
	global_load_dwordx4 v[144:147], v2, s[8:9] offset:2048
	v_lshlrev_b32_e32 v224, 16, v84
	v_and_b32_e32 v225, 0xffff0000, v84
	v_lshlrev_b32_e32 v226, 16, v85
	v_and_b32_e32 v227, 0xffff0000, v85
	v_lshlrev_b32_e32 v228, 16, v86
	v_and_b32_e32 v229, 0xffff0000, v86
	v_lshlrev_b32_e32 v230, 16, v87
	v_and_b32_e32 v231, 0xffff0000, v87
	v_pk_mul_f32 v[224:225], v[214:215], v[224:225]
	v_pk_mul_f32 v[226:227], v[214:215], v[226:227]
	v_pk_mul_f32 v[228:229], v[214:215], v[228:229]
	v_pk_mul_f32 v[230:231], v[214:215], v[230:231]
	v_pk_mul_f32 v[224:225], v[32:33], v[224:225]
	v_pk_mul_f32 v[226:227], v[34:35], v[226:227]
	v_pk_mul_f32 v[228:229], v[36:37], v[228:229]
	v_pk_mul_f32 v[230:231], v[38:39], v[230:231]
	global_store_dwordx4 v3, v[224:227], s[14:15] offset:2048
	global_store_dwordx4 v3, v[228:231], s[14:15] offset:2064
	global_load_dwordx4 v[148:151], v2, s[8:9] offset:3072
	v_lshlrev_b32_e32 v216, 16, v88
	v_and_b32_e32 v217, 0xffff0000, v88
	v_lshlrev_b32_e32 v218, 16, v89
	v_and_b32_e32 v219, 0xffff0000, v89
	v_lshlrev_b32_e32 v220, 16, v90
	v_and_b32_e32 v221, 0xffff0000, v90
	v_lshlrev_b32_e32 v222, 16, v91
	v_and_b32_e32 v223, 0xffff0000, v91
	v_pk_mul_f32 v[216:217], v[214:215], v[216:217]
	v_pk_mul_f32 v[218:219], v[214:215], v[218:219]
	v_pk_mul_f32 v[220:221], v[214:215], v[220:221]
	v_pk_mul_f32 v[222:223], v[214:215], v[222:223]
	v_pk_mul_f32 v[216:217], v[40:41], v[216:217]
	v_pk_mul_f32 v[218:219], v[42:43], v[218:219]
	v_pk_mul_f32 v[220:221], v[44:45], v[220:221]
	v_pk_mul_f32 v[222:223], v[46:47], v[222:223]
	global_store_dwordx4 v3, v[216:219], s[16:17] offset:0
	global_store_dwordx4 v3, v[220:223], s[16:17] offset:16
	global_load_dwordx4 v[152:155], v2, s[10:11] offset:0
	v_lshlrev_b32_e32 v224, 16, v92
	v_and_b32_e32 v225, 0xffff0000, v92
	v_lshlrev_b32_e32 v226, 16, v93
	v_and_b32_e32 v227, 0xffff0000, v93
	v_lshlrev_b32_e32 v228, 16, v94
	v_and_b32_e32 v229, 0xffff0000, v94
	v_lshlrev_b32_e32 v230, 16, v95
	v_and_b32_e32 v231, 0xffff0000, v95
	v_pk_mul_f32 v[224:225], v[214:215], v[224:225]
	v_pk_mul_f32 v[226:227], v[214:215], v[226:227]
	v_pk_mul_f32 v[228:229], v[214:215], v[228:229]
	v_pk_mul_f32 v[230:231], v[214:215], v[230:231]
	v_pk_mul_f32 v[224:225], v[48:49], v[224:225]
	v_pk_mul_f32 v[226:227], v[50:51], v[226:227]
	v_pk_mul_f32 v[228:229], v[52:53], v[228:229]
	v_pk_mul_f32 v[230:231], v[54:55], v[230:231]
	global_store_dwordx4 v3, v[224:227], s[16:17] offset:2048
	global_store_dwordx4 v3, v[228:231], s[16:17] offset:2064
	global_load_dwordx4 v[156:159], v2, s[10:11] offset:1024
	v_lshlrev_b32_e32 v216, 16, v96
	v_and_b32_e32 v217, 0xffff0000, v96
	v_lshlrev_b32_e32 v218, 16, v97
	v_and_b32_e32 v219, 0xffff0000, v97
	v_lshlrev_b32_e32 v220, 16, v98
	v_and_b32_e32 v221, 0xffff0000, v98
	v_lshlrev_b32_e32 v222, 16, v99
	v_and_b32_e32 v223, 0xffff0000, v99
	v_pk_mul_f32 v[216:217], v[214:215], v[216:217]
	v_pk_mul_f32 v[218:219], v[214:215], v[218:219]
	v_pk_mul_f32 v[220:221], v[214:215], v[220:221]
	v_pk_mul_f32 v[222:223], v[214:215], v[222:223]
	v_pk_mul_f32 v[216:217], v[56:57], v[216:217]
	v_pk_mul_f32 v[218:219], v[58:59], v[218:219]
	v_pk_mul_f32 v[220:221], v[60:61], v[220:221]
	v_pk_mul_f32 v[222:223], v[62:63], v[222:223]
	global_store_dwordx4 v3, v[216:219], s[18:19] offset:0
	global_store_dwordx4 v3, v[220:223], s[18:19] offset:16
	global_load_dwordx4 v[160:163], v2, s[10:11] offset:2048
	v_lshlrev_b32_e32 v224, 16, v100
	v_and_b32_e32 v225, 0xffff0000, v100
	v_lshlrev_b32_e32 v226, 16, v101
	v_and_b32_e32 v227, 0xffff0000, v101
	v_lshlrev_b32_e32 v228, 16, v102
	v_and_b32_e32 v229, 0xffff0000, v102
	v_lshlrev_b32_e32 v230, 16, v103
	v_and_b32_e32 v231, 0xffff0000, v103
	v_pk_mul_f32 v[224:225], v[214:215], v[224:225]
	v_pk_mul_f32 v[226:227], v[214:215], v[226:227]
	v_pk_mul_f32 v[228:229], v[214:215], v[228:229]
	v_pk_mul_f32 v[230:231], v[214:215], v[230:231]
	v_pk_mul_f32 v[224:225], v[64:65], v[224:225]
	v_pk_mul_f32 v[226:227], v[66:67], v[226:227]
	v_pk_mul_f32 v[228:229], v[68:69], v[228:229]
	v_pk_mul_f32 v[230:231], v[70:71], v[230:231]
	global_store_dwordx4 v3, v[224:227], s[18:19] offset:2048
	global_store_dwordx4 v3, v[228:231], s[18:19] offset:2064
	global_load_dwordx4 v[164:167], v2, s[10:11] offset:3072
	s_mul_i32 s26, s74, 1
	s_add_i32 s26, s26, s52
	s_lshl_b32 s27, s26, 14
	s_add_u32 s12, s56, s27
	s_addc_u32 s13, s57, 0
	s_add_u32 s14, s12, 0x1000
	s_addc_u32 s15, s13, 0
	s_add_u32 s16, s14, 0x1000
	s_addc_u32 s17, s15, 0
	s_add_u32 s18, s16, 0x1000
	s_addc_u32 s19, s17, 0
	s_waitcnt vmcnt(25)
; __device__ __forceinline__ float bflo(unsigned w) { return __uint_as_float(w << 16); }
; __device__ __forceinline__ float bfhi(unsigned w) { return __uint_as_float(w & 0xffff0000u); }
; __device__ __forceinline__ void phase_final_norm(const bf16_t* Hb, const unsigned long long* ssq, const float* g, float* out, int gw, int ngw, int lane, float scale) {
;     for (int m = gw; m < MTOK; m += ngw) { const float rstd = scale / sqrtf((float)ssq[m] * (1.0f / 16777216.0f) * (1.0f / DM) + EPS);
;         const u32x4* xr = (const u32x4*)(Hb + (size_t)m * DM) + lane; f32x4* o = (f32x4*)(out + (size_t)m * DM); const f32x4* gr = (const f32x4*)g;
; #pragma unroll
;         for (int j = 0; j < 8; ++j) { const u32x4 r = xr[64 * j]; const int c4 = 2 * (64 * j + lane);
;             const f32x4 g0 = gr[c4], g1 = gr[c4 + 1];
;             o[c4] = (f32x4){bflo(r.x) * rstd * g0.x, bfhi(r.x) * rstd * g0.y, bflo(r.y) * rstd * g0.z, bfhi(r.y) * rstd * g0.w};
;             o[c4 + 1] = (f32x4){bflo(r.z) * rstd * g1.x, bfhi(r.z) * rstd * g1.y, bflo(r.w) * rstd * g1.z, bfhi(r.w) * rstd * g1.w}; } }
	v_ffbh_u32_e32 v208, v203
	v_min_u32_e32 v208, 32, v208
	v_lshlrev_b64 v[202:203], v208, v[202:203]
	v_min_u32_e32 v202, 1, v202
	v_or_b32_e32 v202, v203, v202
	v_cvt_f32_u32_e32 v202, v202
	v_sub_u32_e32 v208, 32, v208
	v_ldexp_f32 v208, v202, v208
	v_mul_f32_e32 v208, 0x33800000, v208
	v_fmamk_f32 v208, v208, 0x39800000, v233
	v_mul_f32_e32 v209, 0x4f800000, v208
	v_cmp_gt_f32_e32 vcc, s28, v208
	s_nop 1
	v_cndmask_b32_e32 v208, v208, v209, vcc
	v_sqrt_f32_e32 v209, v208
	s_nop 1
	v_add_u32_e32 v210, -1, v209
	v_add_u32_e32 v211, 1, v209
	v_fma_f32 v212, -v210, v209, v208
	v_fma_f32 v213, -v211, v209, v208
	v_cmp_ge_f32_e64 s[0:1], 0, v212
	s_nop 1
	v_cndmask_b32_e64 v209, v209, v210, s[0:1]
	v_cmp_lt_f32_e64 s[0:1], 0, v213
	s_nop 1
	v_cndmask_b32_e64 v209, v209, v211, s[0:1]
	v_mul_f32_e32 v210, 0x37800000, v209
	v_cndmask_b32_e32 v209, v209, v210, vcc
	v_cmp_class_f32_e32 vcc, v208, v234
	s_nop 1
	v_cndmask_b32_e32 v208, v209, v208, vcc
	v_div_scale_f32 v209, s[0:1], v208, v208, 1.0
	v_rcp_f32_e32 v211, v209
	v_div_scale_f32 v210, vcc, 1.0, v208, 1.0
	s_nop 0
	v_fma_f32 v212, -v209, v211, 1.0
	v_fmac_f32_e32 v211, v212, v211
	v_mul_f32_e32 v212, v210, v211
	v_fma_f32 v213, -v209, v212, v210
	v_fmac_f32_e32 v212, v213, v211
	v_fma_f32 v209, -v209, v212, v210
	s_nop 1
	v_div_fmas_f32 v209, v209, v211, v212
	v_div_fixup_f32 v214, v209, v208, 1.0
	v_mov_b32_e32 v215, v214
	v_lshlrev_b32_e32 v216, 16, v104
	v_and_b32_e32 v217, 0xffff0000, v104
	v_lshlrev_b32_e32 v218, 16, v105
	v_and_b32_e32 v219, 0xffff0000, v105
	v_lshlrev_b32_e32 v220, 16, v106
	v_and_b32_e32 v221, 0xffff0000, v106
	v_lshlrev_b32_e32 v222, 16, v107
	v_and_b32_e32 v223, 0xffff0000, v107
	v_pk_mul_f32 v[216:217], v[214:215], v[216:217]
	v_pk_mul_f32 v[218:219], v[214:215], v[218:219]
	v_pk_mul_f32 v[220:221], v[214:215], v[220:221]
	v_pk_mul_f32 v[222:223], v[214:215], v[222:223]
	v_pk_mul_f32 v[216:217], v[8:9], v[216:217]
	v_pk_mul_f32 v[218:219], v[10:11], v[218:219]
	v_pk_mul_f32 v[220:221], v[12:13], v[220:221]
	v_pk_mul_f32 v[222:223], v[14:15], v[222:223]
	global_store_dwordx4 v3, v[216:219], s[12:13] offset:0
	global_store_dwordx4 v3, v[220:223], s[12:13] offset:16
	s_mul_i32 s29, s74, 3
	s_add_i32 s29, s29, s52
	s_lshl_b32 s27, s29, 3
	s_add_u32 s8, s4, s27
	s_addc_u32 s9, s5, 0
	global_load_dwordx2 v[206:207], v232, s[8:9]
	s_lshl_b32 s27, s29, 13
	s_add_u32 s8, s6, s27
	s_addc_u32 s9, s7, 0
	s_add_u32 s10, s8, 0x1000
	s_addc_u32 s11, s9, 0
	global_load_dwordx4 v[168:171], v2, s[8:9] offset:0
	v_lshlrev_b32_e32 v224, 16, v108
	v_and_b32_e32 v225, 0xffff0000, v108
	v_lshlrev_b32_e32 v226, 16, v109
	v_and_b32_e32 v227, 0xffff0000, v109
	v_lshlrev_b32_e32 v228, 16, v110
	v_and_b32_e32 v229, 0xffff0000, v110
	v_lshlrev_b32_e32 v230, 16, v111
	v_and_b32_e32 v231, 0xffff0000, v111
	v_pk_mul_f32 v[224:225], v[214:215], v[224:225]
	v_pk_mul_f32 v[226:227], v[214:215], v[226:227]
	v_pk_mul_f32 v[228:229], v[214:215], v[228:229]
	v_pk_mul_f32 v[230:231], v[214:215], v[230:231]
	v_pk_mul_f32 v[224:225], v[16:17], v[224:225]
	v_pk_mul_f32 v[226:227], v[18:19], v[226:227]
	v_pk_mul_f32 v[228:229], v[20:21], v[228:229]
	v_pk_mul_f32 v[230:231], v[22:23], v[230:231]
	global_store_dwordx4 v3, v[224:227], s[12:13] offset:2048
	global_store_dwordx4 v3, v[228:231], s[12:13] offset:2064
	global_load_dwordx4 v[172:175], v2, s[8:9] offset:1024
	v_lshlrev_b32_e32 v216, 16, v112
	v_and_b32_e32 v217, 0xffff0000, v112
	v_lshlrev_b32_e32 v218, 16, v113
	v_and_b32_e32 v219, 0xffff0000, v113
	v_lshlrev_b32_e32 v220, 16, v114
	v_and_b32_e32 v221, 0xffff0000, v114
	v_lshlrev_b32_e32 v222, 16, v115
	v_and_b32_e32 v223, 0xffff0000, v115
	v_pk_mul_f32 v[216:217], v[214:215], v[216:217]
	v_pk_mul_f32 v[218:219], v[214:215], v[218:219]
	v_pk_mul_f32 v[220:221], v[214:215], v[220:221]
	v_pk_mul_f32 v[222:223], v[214:215], v[222:223]
	v_pk_mul_f32 v[216:217], v[24:25], v[216:217]
	v_pk_mul_f32 v[218:219], v[26:27], v[218:219]
	v_pk_mul_f32 v[220:221], v[28:29], v[220:221]
	v_pk_mul_f32 v[222:223], v[30:31], v[222:223]
	global_store_dwordx4 v3, v[216:219], s[14:15] offset:0
	global_store_dwordx4 v3, v[220:223], s[14:15] offset:16
	global_load_dwordx4 v[176:179], v2, s[8:9] offset:2048
	v_lshlrev_b32_e32 v224, 16, v116
	v_and_b32_e32 v225, 0xffff0000, v116
	v_lshlrev_b32_e32 v226, 16, v117
	v_and_b32_e32 v227, 0xffff0000, v117
	v_lshlrev_b32_e32 v228, 16, v118
	v_and_b32_e32 v229, 0xffff0000, v118
	v_lshlrev_b32_e32 v230, 16, v119
	v_and_b32_e32 v231, 0xffff0000, v119
	v_pk_mul_f32 v[224:225], v[214:215], v[224:225]
	v_pk_mul_f32 v[226:227], v[214:215], v[226:227]
	v_pk_mul_f32 v[228:229], v[214:215], v[228:229]
	v_pk_mul_f32 v[230:231], v[214:215], v[230:231]
	v_pk_mul_f32 v[224:225], v[32:33], v[224:225]
	v_pk_mul_f32 v[226:227], v[34:35], v[226:227]
	v_pk_mul_f32 v[228:229], v[36:37], v[228:229]
	v_pk_mul_f32 v[230:231], v[38:39], v[230:231]
	global_store_dwordx4 v3, v[224:227], s[14:15] offset:2048
	global_store_dwordx4 v3, v[228:231], s[14:15] offset:2064
	global_load_dwordx4 v[180:183], v2, s[8:9] offset:3072
	v_lshlrev_b32_e32 v216, 16, v120
	v_and_b32_e32 v217, 0xffff0000, v120
	v_lshlrev_b32_e32 v218, 16, v121
	v_and_b32_e32 v219, 0xffff0000, v121
	v_lshlrev_b32_e32 v220, 16, v122
	v_and_b32_e32 v221, 0xffff0000, v122
	v_lshlrev_b32_e32 v222, 16, v123
	v_and_b32_e32 v223, 0xffff0000, v123
	v_pk_mul_f32 v[216:217], v[214:215], v[216:217]
	v_pk_mul_f32 v[218:219], v[214:215], v[218:219]
	v_pk_mul_f32 v[220:221], v[214:215], v[220:221]
	v_pk_mul_f32 v[222:223], v[214:215], v[222:223]
	v_pk_mul_f32 v[216:217], v[40:41], v[216:217]
	v_pk_mul_f32 v[218:219], v[42:43], v[218:219]
; __device__ __forceinline__ float bflo(unsigned w) { return __uint_as_float(w << 16); }
; __device__ __forceinline__ float bfhi(unsigned w) { return __uint_as_float(w & 0xffff0000u); }
; __device__ __forceinline__ void phase_final_norm(const bf16_t* Hb, const unsigned long long* ssq, const float* g, float* out, int gw, int ngw, int lane, float scale) {
;     for (int m = gw; m < MTOK; m += ngw) { const float rstd = scale / sqrtf((float)ssq[m] * (1.0f / 16777216.0f) * (1.0f / DM) + EPS);
;         const u32x4* xr = (const u32x4*)(Hb + (size_t)m * DM) + lane; f32x4* o = (f32x4*)(out + (size_t)m * DM); const f32x4* gr = (const f32x4*)g;
; #pragma unroll
;         for (int j = 0; j < 8; ++j) { const u32x4 r = xr[64 * j]; const int c4 = 2 * (64 * j + lane);
;             const f32x4 g0 = gr[c4], g1 = gr[c4 + 1];
;             o[c4] = (f32x4){bflo(r.x) * rstd * g0.x, bfhi(r.x) * rstd * g0.y, bflo(r.y) * rstd * g0.z, bfhi(r.y) * rstd * g0.w};
;             o[c4 + 1] = (f32x4){bflo(r.z) * rstd * g1.x, bfhi(r.z) * rstd * g1.y, bflo(r.w) * rstd * g1.z, bfhi(r.w) * rstd * g1.w}; } }
	v_pk_mul_f32 v[220:221], v[44:45], v[220:221]
	v_pk_mul_f32 v[222:223], v[46:47], v[222:223]
	global_store_dwordx4 v3, v[216:219], s[16:17] offset:0
	global_store_dwordx4 v3, v[220:223], s[16:17] offset:16
	global_load_dwordx4 v[184:187], v2, s[10:11] offset:0
	v_lshlrev_b32_e32 v224, 16, v124
	v_and_b32_e32 v225, 0xffff0000, v124
	v_lshlrev_b32_e32 v226, 16, v125
	v_and_b32_e32 v227, 0xffff0000, v125
	v_lshlrev_b32_e32 v228, 16, v126
	v_and_b32_e32 v229, 0xffff0000, v126
	v_lshlrev_b32_e32 v230, 16, v127
	v_and_b32_e32 v231, 0xffff0000, v127
	v_pk_mul_f32 v[224:225], v[214:215], v[224:225]
	v_pk_mul_f32 v[226:227], v[214:215], v[226:227]
	v_pk_mul_f32 v[228:229], v[214:215], v[228:229]
	v_pk_mul_f32 v[230:231], v[214:215], v[230:231]
	v_pk_mul_f32 v[224:225], v[48:49], v[224:225]
	v_pk_mul_f32 v[226:227], v[50:51], v[226:227]
	v_pk_mul_f32 v[228:229], v[52:53], v[228:229]
	v_pk_mul_f32 v[230:231], v[54:55], v[230:231]
	global_store_dwordx4 v3, v[224:227], s[16:17] offset:2048
	global_store_dwordx4 v3, v[228:231], s[16:17] offset:2064
	global_load_dwordx4 v[188:191], v2, s[10:11] offset:1024
	v_lshlrev_b32_e32 v216, 16, v128
	v_and_b32_e32 v217, 0xffff0000, v128
	v_lshlrev_b32_e32 v218, 16, v129
	v_and_b32_e32 v219, 0xffff0000, v129
	v_lshlrev_b32_e32 v220, 16, v130
	v_and_b32_e32 v221, 0xffff0000, v130
	v_lshlrev_b32_e32 v222, 16, v131
	v_and_b32_e32 v223, 0xffff0000, v131
	v_pk_mul_f32 v[216:217], v[214:215], v[216:217]
	v_pk_mul_f32 v[218:219], v[214:215], v[218:219]
	v_pk_mul_f32 v[220:221], v[214:215], v[220:221]
	v_pk_mul_f32 v[222:223], v[214:215], v[222:223]
	v_pk_mul_f32 v[216:217], v[56:57], v[216:217]
	v_pk_mul_f32 v[218:219], v[58:59], v[218:219]
	v_pk_mul_f32 v[220:221], v[60:61], v[220:221]
	v_pk_mul_f32 v[222:223], v[62:63], v[222:223]
	global_store_dwordx4 v3, v[216:219], s[18:19] offset:0
	global_store_dwordx4 v3, v[220:223], s[18:19] offset:16
	global_load_dwordx4 v[192:195], v2, s[10:11] offset:2048
	v_lshlrev_b32_e32 v224, 16, v132
	v_and_b32_e32 v225, 0xffff0000, v132
	v_lshlrev_b32_e32 v226, 16, v133
	v_and_b32_e32 v227, 0xffff0000, v133
	v_lshlrev_b32_e32 v228, 16, v134
	v_and_b32_e32 v229, 0xffff0000, v134
	v_lshlrev_b32_e32 v230, 16, v135
	v_and_b32_e32 v231, 0xffff0000, v135
	v_pk_mul_f32 v[224:225], v[214:215], v[224:225]
	v_pk_mul_f32 v[226:227], v[214:215], v[226:227]
	v_pk_mul_f32 v[228:229], v[214:215], v[228:229]
	v_pk_mul_f32 v[230:231], v[214:215], v[230:231]
	v_pk_mul_f32 v[224:225], v[64:65], v[224:225]
	v_pk_mul_f32 v[226:227], v[66:67], v[226:227]
	v_pk_mul_f32 v[228:229], v[68:69], v[228:229]
	v_pk_mul_f32 v[230:231], v[70:71], v[230:231]
	global_store_dwordx4 v3, v[224:227], s[18:19] offset:2048
	global_store_dwordx4 v3, v[228:231], s[18:19] offset:2064
	global_load_dwordx4 v[196:199], v2, s[10:11] offset:3072
	s_mul_i32 s26, s74, 2
	s_add_i32 s26, s26, s52
	s_lshl_b32 s27, s26, 14
	s_add_u32 s12, s56, s27
	s_addc_u32 s13, s57, 0
	s_add_u32 s14, s12, 0x1000
	s_addc_u32 s15, s13, 0
	s_add_u32 s16, s14, 0x1000
	s_addc_u32 s17, s15, 0
	s_add_u32 s18, s16, 0x1000
	s_addc_u32 s19, s17, 0
	s_waitcnt vmcnt(25)
	v_ffbh_u32_e32 v208, v205
	v_min_u32_e32 v208, 32, v208
	v_lshlrev_b64 v[204:205], v208, v[204:205]
	v_min_u32_e32 v204, 1, v204
	v_or_b32_e32 v204, v205, v204
	v_cvt_f32_u32_e32 v204, v204
	v_sub_u32_e32 v208, 32, v208
	v_ldexp_f32 v208, v204, v208
	v_mul_f32_e32 v208, 0x33800000, v208
	v_fmamk_f32 v208, v208, 0x39800000, v233
	v_mul_f32_e32 v209, 0x4f800000, v208
	v_cmp_gt_f32_e32 vcc, s28, v208
	s_nop 1
	v_cndmask_b32_e32 v208, v208, v209, vcc
	v_sqrt_f32_e32 v209, v208
	s_nop 1
	v_add_u32_e32 v210, -1, v209
	v_add_u32_e32 v211, 1, v209
	v_fma_f32 v212, -v210, v209, v208
	v_fma_f32 v213, -v211, v209, v208
	v_cmp_ge_f32_e64 s[0:1], 0, v212
	s_nop 1
	v_cndmask_b32_e64 v209, v209, v210, s[0:1]
	v_cmp_lt_f32_e64 s[0:1], 0, v213
	s_nop 1
	v_cndmask_b32_e64 v209, v209, v211, s[0:1]
	v_mul_f32_e32 v210, 0x37800000, v209
	v_cndmask_b32_e32 v209, v209, v210, vcc
	v_cmp_class_f32_e32 vcc, v208, v234
	s_nop 1
	v_cndmask_b32_e32 v208, v209, v208, vcc
	v_div_scale_f32 v209, s[0:1], v208, v208, 1.0
	v_rcp_f32_e32 v211, v209
	v_div_scale_f32 v210, vcc, 1.0, v208, 1.0
	s_nop 0
	v_fma_f32 v212, -v209, v211, 1.0
	v_fmac_f32_e32 v211, v212, v211
	v_mul_f32_e32 v212, v210, v211
	v_fma_f32 v213, -v209, v212, v210
	v_fmac_f32_e32 v212, v213, v211
	v_fma_f32 v209, -v209, v212, v210
	s_nop 1
	v_div_fmas_f32 v209, v209, v211, v212
	v_div_fixup_f32 v214, v209, v208, 1.0
	v_mov_b32_e32 v215, v214
	v_lshlrev_b32_e32 v216, 16, v136
	v_and_b32_e32 v217, 0xffff0000, v136
	v_lshlrev_b32_e32 v218, 16, v137
	v_and_b32_e32 v219, 0xffff0000, v137
	v_lshlrev_b32_e32 v220, 16, v138
	v_and_b32_e32 v221, 0xffff0000, v138
	v_lshlrev_b32_e32 v222, 16, v139
	v_and_b32_e32 v223, 0xffff0000, v139
	v_pk_mul_f32 v[216:217], v[214:215], v[216:217]
	v_pk_mul_f32 v[218:219], v[214:215], v[218:219]
	v_pk_mul_f32 v[220:221], v[214:215], v[220:221]
	v_pk_mul_f32 v[222:223], v[214:215], v[222:223]
	v_pk_mul_f32 v[216:217], v[8:9], v[216:217]
	v_pk_mul_f32 v[218:219], v[10:11], v[218:219]
	v_pk_mul_f32 v[220:221], v[12:13], v[220:221]
	v_pk_mul_f32 v[222:223], v[14:15], v[222:223]
	global_store_dwordx4 v3, v[216:219], s[12:13] offset:0
	global_store_dwordx4 v3, v[220:223], s[12:13] offset:16
	v_lshlrev_b32_e32 v224, 16, v140
	v_and_b32_e32 v225, 0xffff0000, v140
	v_lshlrev_b32_e32 v226, 16, v141
	v_and_b32_e32 v227, 0xffff0000, v141
	v_lshlrev_b32_e32 v228, 16, v142
	v_and_b32_e32 v229, 0xffff0000, v142
	v_lshlrev_b32_e32 v230, 16, v143
	v_and_b32_e32 v231, 0xffff0000, v143
	v_pk_mul_f32 v[224:225], v[214:215], v[224:225]
; __device__ __forceinline__ float bflo(unsigned w) { return __uint_as_float(w << 16); }
; __device__ __forceinline__ float bfhi(unsigned w) { return __uint_as_float(w & 0xffff0000u); }
; __device__ __forceinline__ void phase_final_norm(const bf16_t* Hb, const unsigned long long* ssq, const float* g, float* out, int gw, int ngw, int lane, float scale) {
;     for (int m = gw; m < MTOK; m += ngw) { const float rstd = scale / sqrtf((float)ssq[m] * (1.0f / 16777216.0f) * (1.0f / DM) + EPS);
;         const u32x4* xr = (const u32x4*)(Hb + (size_t)m * DM) + lane; f32x4* o = (f32x4*)(out + (size_t)m * DM); const f32x4* gr = (const f32x4*)g;
; #pragma unroll
;         for (int j = 0; j < 8; ++j) { const u32x4 r = xr[64 * j]; const int c4 = 2 * (64 * j + lane);
;             const f32x4 g0 = gr[c4], g1 = gr[c4 + 1];
;             o[c4] = (f32x4){bflo(r.x) * rstd * g0.x, bfhi(r.x) * rstd * g0.y, bflo(r.y) * rstd * g0.z, bfhi(r.y) * rstd * g0.w};
;             o[c4 + 1] = (f32x4){bflo(r.z) * rstd * g1.x, bfhi(r.z) * rstd * g1.y, bflo(r.w) * rstd * g1.z, bfhi(r.w) * rstd * g1.w}; } }
	v_pk_mul_f32 v[226:227], v[214:215], v[226:227]
	v_pk_mul_f32 v[228:229], v[214:215], v[228:229]
	v_pk_mul_f32 v[230:231], v[214:215], v[230:231]
	v_pk_mul_f32 v[224:225], v[16:17], v[224:225]
	v_pk_mul_f32 v[226:227], v[18:19], v[226:227]
	v_pk_mul_f32 v[228:229], v[20:21], v[228:229]
	v_pk_mul_f32 v[230:231], v[22:23], v[230:231]
	global_store_dwordx4 v3, v[224:227], s[12:13] offset:2048
	global_store_dwordx4 v3, v[228:231], s[12:13] offset:2064
	v_lshlrev_b32_e32 v216, 16, v144
	v_and_b32_e32 v217, 0xffff0000, v144
	v_lshlrev_b32_e32 v218, 16, v145
	v_and_b32_e32 v219, 0xffff0000, v145
	v_lshlrev_b32_e32 v220, 16, v146
	v_and_b32_e32 v221, 0xffff0000, v146
	v_lshlrev_b32_e32 v222, 16, v147
	v_and_b32_e32 v223, 0xffff0000, v147
	v_pk_mul_f32 v[216:217], v[214:215], v[216:217]
	v_pk_mul_f32 v[218:219], v[214:215], v[218:219]
	v_pk_mul_f32 v[220:221], v[214:215], v[220:221]
	v_pk_mul_f32 v[222:223], v[214:215], v[222:223]
	v_pk_mul_f32 v[216:217], v[24:25], v[216:217]
	v_pk_mul_f32 v[218:219], v[26:27], v[218:219]
	v_pk_mul_f32 v[220:221], v[28:29], v[220:221]
	v_pk_mul_f32 v[222:223], v[30:31], v[222:223]
	global_store_dwordx4 v3, v[216:219], s[14:15] offset:0
	global_store_dwordx4 v3, v[220:223], s[14:15] offset:16
	v_lshlrev_b32_e32 v224, 16, v148
	v_and_b32_e32 v225, 0xffff0000, v148
	v_lshlrev_b32_e32 v226, 16, v149
	v_and_b32_e32 v227, 0xffff0000, v149
	v_lshlrev_b32_e32 v228, 16, v150
	v_and_b32_e32 v229, 0xffff0000, v150
	v_lshlrev_b32_e32 v230, 16, v151
	v_and_b32_e32 v231, 0xffff0000, v151
	v_pk_mul_f32 v[224:225], v[214:215], v[224:225]
	v_pk_mul_f32 v[226:227], v[214:215], v[226:227]
	v_pk_mul_f32 v[228:229], v[214:215], v[228:229]
	v_pk_mul_f32 v[230:231], v[214:215], v[230:231]
	v_pk_mul_f32 v[224:225], v[32:33], v[224:225]
	v_pk_mul_f32 v[226:227], v[34:35], v[226:227]
	v_pk_mul_f32 v[228:229], v[36:37], v[228:229]
	v_pk_mul_f32 v[230:231], v[38:39], v[230:231]
	global_store_dwordx4 v3, v[224:227], s[14:15] offset:2048
	global_store_dwordx4 v3, v[228:231], s[14:15] offset:2064
	v_lshlrev_b32_e32 v216, 16, v152
	v_and_b32_e32 v217, 0xffff0000, v152
	v_lshlrev_b32_e32 v218, 16, v153
	v_and_b32_e32 v219, 0xffff0000, v153
	v_lshlrev_b32_e32 v220, 16, v154
	v_and_b32_e32 v221, 0xffff0000, v154
	v_lshlrev_b32_e32 v222, 16, v155
	v_and_b32_e32 v223, 0xffff0000, v155
	v_pk_mul_f32 v[216:217], v[214:215], v[216:217]
	v_pk_mul_f32 v[218:219], v[214:215], v[218:219]
	v_pk_mul_f32 v[220:221], v[214:215], v[220:221]
	v_pk_mul_f32 v[222:223], v[214:215], v[222:223]
	v_pk_mul_f32 v[216:217], v[40:41], v[216:217]
	v_pk_mul_f32 v[218:219], v[42:43], v[218:219]
	v_pk_mul_f32 v[220:221], v[44:45], v[220:221]
	v_pk_mul_f32 v[222:223], v[46:47], v[222:223]
	global_store_dwordx4 v3, v[216:219], s[16:17] offset:0
	global_store_dwordx4 v3, v[220:223], s[16:17] offset:16
	v_lshlrev_b32_e32 v224, 16, v156
	v_and_b32_e32 v225, 0xffff0000, v156
	v_lshlrev_b32_e32 v226, 16, v157
	v_and_b32_e32 v227, 0xffff0000, v157
	v_lshlrev_b32_e32 v228, 16, v158
	v_and_b32_e32 v229, 0xffff0000, v158
	v_lshlrev_b32_e32 v230, 16, v159
	v_and_b32_e32 v231, 0xffff0000, v159
	v_pk_mul_f32 v[224:225], v[214:215], v[224:225]
	v_pk_mul_f32 v[226:227], v[214:215], v[226:227]
	v_pk_mul_f32 v[228:229], v[214:215], v[228:229]
	v_pk_mul_f32 v[230:231], v[214:215], v[230:231]
	v_pk_mul_f32 v[224:225], v[48:49], v[224:225]
	v_pk_mul_f32 v[226:227], v[50:51], v[226:227]
	v_pk_mul_f32 v[228:229], v[52:53], v[228:229]
	v_pk_mul_f32 v[230:231], v[54:55], v[230:231]
	global_store_dwordx4 v3, v[224:227], s[16:17] offset:2048
	global_store_dwordx4 v3, v[228:231], s[16:17] offset:2064
	v_lshlrev_b32_e32 v216, 16, v160
	v_and_b32_e32 v217, 0xffff0000, v160
	v_lshlrev_b32_e32 v218, 16, v161
	v_and_b32_e32 v219, 0xffff0000, v161
	v_lshlrev_b32_e32 v220, 16, v162
	v_and_b32_e32 v221, 0xffff0000, v162
	v_lshlrev_b32_e32 v222, 16, v163
	v_and_b32_e32 v223, 0xffff0000, v163
	v_pk_mul_f32 v[216:217], v[214:215], v[216:217]
	v_pk_mul_f32 v[218:219], v[214:215], v[218:219]
	v_pk_mul_f32 v[220:221], v[214:215], v[220:221]
	v_pk_mul_f32 v[222:223], v[214:215], v[222:223]
	v_pk_mul_f32 v[216:217], v[56:57], v[216:217]
	v_pk_mul_f32 v[218:219], v[58:59], v[218:219]
	v_pk_mul_f32 v[220:221], v[60:61], v[220:221]
	v_pk_mul_f32 v[222:223], v[62:63], v[222:223]
	global_store_dwordx4 v3, v[216:219], s[18:19] offset:0
	global_store_dwordx4 v3, v[220:223], s[18:19] offset:16
	v_lshlrev_b32_e32 v224, 16, v164
	v_and_b32_e32 v225, 0xffff0000, v164
	v_lshlrev_b32_e32 v226, 16, v165
	v_and_b32_e32 v227, 0xffff0000, v165
	v_lshlrev_b32_e32 v228, 16, v166
	v_and_b32_e32 v229, 0xffff0000, v166
	v_lshlrev_b32_e32 v230, 16, v167
	v_and_b32_e32 v231, 0xffff0000, v167
	v_pk_mul_f32 v[224:225], v[214:215], v[224:225]
	v_pk_mul_f32 v[226:227], v[214:215], v[226:227]
	v_pk_mul_f32 v[228:229], v[214:215], v[228:229]
	v_pk_mul_f32 v[230:231], v[214:215], v[230:231]
	v_pk_mul_f32 v[224:225], v[64:65], v[224:225]
	v_pk_mul_f32 v[226:227], v[66:67], v[226:227]
	v_pk_mul_f32 v[228:229], v[68:69], v[228:229]
	v_pk_mul_f32 v[230:231], v[70:71], v[230:231]
	global_store_dwordx4 v3, v[224:227], s[18:19] offset:2048
	global_store_dwordx4 v3, v[228:231], s[18:19] offset:2064
	s_mul_i32 s26, s74, 3
	s_add_i32 s26, s26, s52
	s_lshl_b32 s27, s26, 14
	s_add_u32 s12, s56, s27
	s_addc_u32 s13, s57, 0
	s_add_u32 s14, s12, 0x1000
	s_addc_u32 s15, s13, 0
	s_add_u32 s16, s14, 0x1000
	s_addc_u32 s17, s15, 0
	s_add_u32 s18, s16, 0x1000
	s_addc_u32 s19, s17, 0
	s_waitcnt vmcnt(16)
; __device__ __forceinline__ float bflo(unsigned w) { return __uint_as_float(w << 16); }
; __device__ __forceinline__ float bfhi(unsigned w) { return __uint_as_float(w & 0xffff0000u); }
; __device__ __forceinline__ void phase_final_norm(const bf16_t* Hb, const unsigned long long* ssq, const float* g, float* out, int gw, int ngw, int lane, float scale) {
;     for (int m = gw; m < MTOK; m += ngw) { const float rstd = scale / sqrtf((float)ssq[m] * (1.0f / 16777216.0f) * (1.0f / DM) + EPS);
;         const u32x4* xr = (const u32x4*)(Hb + (size_t)m * DM) + lane; f32x4* o = (f32x4*)(out + (size_t)m * DM); const f32x4* gr = (const f32x4*)g;
; #pragma unroll
;         for (int j = 0; j < 8; ++j) { const u32x4 r = xr[64 * j]; const int c4 = 2 * (64 * j + lane);
;             const f32x4 g0 = gr[c4], g1 = gr[c4 + 1];
;             o[c4] = (f32x4){bflo(r.x) * rstd * g0.x, bfhi(r.x) * rstd * g0.y, bflo(r.y) * rstd * g0.z, bfhi(r.y) * rstd * g0.w};
;             o[c4 + 1] = (f32x4){bflo(r.z) * rstd * g1.x, bfhi(r.z) * rstd * g1.y, bflo(r.w) * rstd * g1.z, bfhi(r.w) * rstd * g1.w}; } }
	v_ffbh_u32_e32 v208, v207
	v_min_u32_e32 v208, 32, v208
	v_lshlrev_b64 v[206:207], v208, v[206:207]
	v_min_u32_e32 v206, 1, v206
	v_or_b32_e32 v206, v207, v206
	v_cvt_f32_u32_e32 v206, v206
	v_sub_u32_e32 v208, 32, v208
	v_ldexp_f32 v208, v206, v208
	v_mul_f32_e32 v208, 0x33800000, v208
	v_fmamk_f32 v208, v208, 0x39800000, v233
	v_mul_f32_e32 v209, 0x4f800000, v208
	v_cmp_gt_f32_e32 vcc, s28, v208
	s_nop 1
	v_cndmask_b32_e32 v208, v208, v209, vcc
	v_sqrt_f32_e32 v209, v208
	s_nop 1
	v_add_u32_e32 v210, -1, v209
	v_add_u32_e32 v211, 1, v209
	v_fma_f32 v212, -v210, v209, v208
	v_fma_f32 v213, -v211, v209, v208
	v_cmp_ge_f32_e64 s[0:1], 0, v212
	s_nop 1
	v_cndmask_b32_e64 v209, v209, v210, s[0:1]
	v_cmp_lt_f32_e64 s[0:1], 0, v213
	s_nop 1
	v_cndmask_b32_e64 v209, v209, v211, s[0:1]
	v_mul_f32_e32 v210, 0x37800000, v209
	v_cndmask_b32_e32 v209, v209, v210, vcc
	v_cmp_class_f32_e32 vcc, v208, v234
	s_nop 1
	v_cndmask_b32_e32 v208, v209, v208, vcc
	v_div_scale_f32 v209, s[0:1], v208, v208, 1.0
	v_rcp_f32_e32 v211, v209
	v_div_scale_f32 v210, vcc, 1.0, v208, 1.0
	s_nop 0
	v_fma_f32 v212, -v209, v211, 1.0
	v_fmac_f32_e32 v211, v212, v211
	v_mul_f32_e32 v212, v210, v211
	v_fma_f32 v213, -v209, v212, v210
	v_fmac_f32_e32 v212, v213, v211
	v_fma_f32 v209, -v209, v212, v210
	s_nop 1
	v_div_fmas_f32 v209, v209, v211, v212
	v_div_fixup_f32 v214, v209, v208, 1.0
	v_mov_b32_e32 v215, v214
	v_lshlrev_b32_e32 v216, 16, v168
	v_and_b32_e32 v217, 0xffff0000, v168
	v_lshlrev_b32_e32 v218, 16, v169
	v_and_b32_e32 v219, 0xffff0000, v169
	v_lshlrev_b32_e32 v220, 16, v170
	v_and_b32_e32 v221, 0xffff0000, v170
	v_lshlrev_b32_e32 v222, 16, v171
	v_and_b32_e32 v223, 0xffff0000, v171
	v_pk_mul_f32 v[216:217], v[214:215], v[216:217]
	v_pk_mul_f32 v[218:219], v[214:215], v[218:219]
	v_pk_mul_f32 v[220:221], v[214:215], v[220:221]
	v_pk_mul_f32 v[222:223], v[214:215], v[222:223]
	v_pk_mul_f32 v[216:217], v[8:9], v[216:217]
	v_pk_mul_f32 v[218:219], v[10:11], v[218:219]
	v_pk_mul_f32 v[220:221], v[12:13], v[220:221]
	v_pk_mul_f32 v[222:223], v[14:15], v[222:223]
	global_store_dwordx4 v3, v[216:219], s[12:13] offset:0
	global_store_dwordx4 v3, v[220:223], s[12:13] offset:16
	v_lshlrev_b32_e32 v224, 16, v172
	v_and_b32_e32 v225, 0xffff0000, v172
	v_lshlrev_b32_e32 v226, 16, v173
	v_and_b32_e32 v227, 0xffff0000, v173
	v_lshlrev_b32_e32 v228, 16, v174
	v_and_b32_e32 v229, 0xffff0000, v174
	v_lshlrev_b32_e32 v230, 16, v175
	v_and_b32_e32 v231, 0xffff0000, v175
	v_pk_mul_f32 v[224:225], v[214:215], v[224:225]
	v_pk_mul_f32 v[226:227], v[214:215], v[226:227]
	v_pk_mul_f32 v[228:229], v[214:215], v[228:229]
	v_pk_mul_f32 v[230:231], v[214:215], v[230:231]
	v_pk_mul_f32 v[224:225], v[16:17], v[224:225]
	v_pk_mul_f32 v[226:227], v[18:19], v[226:227]
	v_pk_mul_f32 v[228:229], v[20:21], v[228:229]
	v_pk_mul_f32 v[230:231], v[22:23], v[230:231]
	global_store_dwordx4 v3, v[224:227], s[12:13] offset:2048
	global_store_dwordx4 v3, v[228:231], s[12:13] offset:2064
	v_lshlrev_b32_e32 v216, 16, v176
	v_and_b32_e32 v217, 0xffff0000, v176
	v_lshlrev_b32_e32 v218, 16, v177
	v_and_b32_e32 v219, 0xffff0000, v177
	v_lshlrev_b32_e32 v220, 16, v178
	v_and_b32_e32 v221, 0xffff0000, v178
	v_lshlrev_b32_e32 v222, 16, v179
	v_and_b32_e32 v223, 0xffff0000, v179
	v_pk_mul_f32 v[216:217], v[214:215], v[216:217]
	v_pk_mul_f32 v[218:219], v[214:215], v[218:219]
	v_pk_mul_f32 v[220:221], v[214:215], v[220:221]
	v_pk_mul_f32 v[222:223], v[214:215], v[222:223]
	v_pk_mul_f32 v[216:217], v[24:25], v[216:217]
	v_pk_mul_f32 v[218:219], v[26:27], v[218:219]
	v_pk_mul_f32 v[220:221], v[28:29], v[220:221]
	v_pk_mul_f32 v[222:223], v[30:31], v[222:223]
	global_store_dwordx4 v3, v[216:219], s[14:15] offset:0
	global_store_dwordx4 v3, v[220:223], s[14:15] offset:16
	v_lshlrev_b32_e32 v224, 16, v180
	v_and_b32_e32 v225, 0xffff0000, v180
	v_lshlrev_b32_e32 v226, 16, v181
; __device__ __forceinline__ float bflo(unsigned w) { return __uint_as_float(w << 16); }
; __device__ __forceinline__ float bfhi(unsigned w) { return __uint_as_float(w & 0xffff0000u); }
; __device__ __forceinline__ void phase_final_norm(const bf16_t* Hb, const unsigned long long* ssq, const float* g, float* out, int gw, int ngw, int lane, float scale) {
;     ...
;         for (int j = 0; j < 8; ++j) { const u32x4 r = xr[64 * j]; const int c4 = 2 * (64 * j + lane);
;             const f32x4 g0 = gr[c4], g1 = gr[c4 + 1];
;             o[c4] = (f32x4){bflo(r.x) * rstd * g0.x, bfhi(r.x) * rstd * g0.y, bflo(r.y) * rstd * g0.z, bfhi(r.y) * rstd * g0.w};
;             o[c4 + 1] = (f32x4){bflo(r.z) * rstd * g1.x, bfhi(r.z) * rstd * g1.y, bflo(r.w) * rstd * g1.z, bfhi(r.w) * rstd * g1.w}; } }
	v_and_b32_e32 v227, 0xffff0000, v181
	v_lshlrev_b32_e32 v228, 16, v182
	v_and_b32_e32 v229, 0xffff0000, v182
	v_lshlrev_b32_e32 v230, 16, v183
	v_and_b32_e32 v231, 0xffff0000, v183
	v_pk_mul_f32 v[224:225], v[214:215], v[224:225]
	v_pk_mul_f32 v[226:227], v[214:215], v[226:227]
	v_pk_mul_f32 v[228:229], v[214:215], v[228:229]
	v_pk_mul_f32 v[230:231], v[214:215], v[230:231]
	v_pk_mul_f32 v[224:225], v[32:33], v[224:225]
	v_pk_mul_f32 v[226:227], v[34:35], v[226:227]
	v_pk_mul_f32 v[228:229], v[36:37], v[228:229]
	v_pk_mul_f32 v[230:231], v[38:39], v[230:231]
	global_store_dwordx4 v3, v[224:227], s[14:15] offset:2048
	global_store_dwordx4 v3, v[228:231], s[14:15] offset:2064
	v_lshlrev_b32_e32 v216, 16, v184
	v_and_b32_e32 v217, 0xffff0000, v184
	v_lshlrev_b32_e32 v218, 16, v185
	v_and_b32_e32 v219, 0xffff0000, v185
	v_lshlrev_b32_e32 v220, 16, v186
	v_and_b32_e32 v221, 0xffff0000, v186
	v_lshlrev_b32_e32 v222, 16, v187
	v_and_b32_e32 v223, 0xffff0000, v187
	v_pk_mul_f32 v[216:217], v[214:215], v[216:217]
	v_pk_mul_f32 v[218:219], v[214:215], v[218:219]
	v_pk_mul_f32 v[220:221], v[214:215], v[220:221]
	v_pk_mul_f32 v[222:223], v[214:215], v[222:223]
	v_pk_mul_f32 v[216:217], v[40:41], v[216:217]
	v_pk_mul_f32 v[218:219], v[42:43], v[218:219]
	v_pk_mul_f32 v[220:221], v[44:45], v[220:221]
	v_pk_mul_f32 v[222:223], v[46:47], v[222:223]
	global_store_dwordx4 v3, v[216:219], s[16:17] offset:0
	global_store_dwordx4 v3, v[220:223], s[16:17] offset:16
	v_lshlrev_b32_e32 v224, 16, v188
	v_and_b32_e32 v225, 0xffff0000, v188
	v_lshlrev_b32_e32 v226, 16, v189
	v_and_b32_e32 v227, 0xffff0000, v189
	v_lshlrev_b32_e32 v228, 16, v190
	v_and_b32_e32 v229, 0xffff0000, v190
	v_lshlrev_b32_e32 v230, 16, v191
	v_and_b32_e32 v231, 0xffff0000, v191
	v_pk_mul_f32 v[224:225], v[214:215], v[224:225]
	v_pk_mul_f32 v[226:227], v[214:215], v[226:227]
	v_pk_mul_f32 v[228:229], v[214:215], v[228:229]
	v_pk_mul_f32 v[230:231], v[214:215], v[230:231]
	v_pk_mul_f32 v[224:225], v[48:49], v[224:225]
	v_pk_mul_f32 v[226:227], v[50:51], v[226:227]
	v_pk_mul_f32 v[228:229], v[52:53], v[228:229]
	v_pk_mul_f32 v[230:231], v[54:55], v[230:231]
	global_store_dwordx4 v3, v[224:227], s[16:17] offset:2048
	global_store_dwordx4 v3, v[228:231], s[16:17] offset:2064
	v_lshlrev_b32_e32 v216, 16, v192
	v_and_b32_e32 v217, 0xffff0000, v192
	v_lshlrev_b32_e32 v218, 16, v193
	v_and_b32_e32 v219, 0xffff0000, v193
	v_lshlrev_b32_e32 v220, 16, v194
	v_and_b32_e32 v221, 0xffff0000, v194
	v_lshlrev_b32_e32 v222, 16, v195
	v_and_b32_e32 v223, 0xffff0000, v195
	v_pk_mul_f32 v[216:217], v[214:215], v[216:217]
	v_pk_mul_f32 v[218:219], v[214:215], v[218:219]
	v_pk_mul_f32 v[220:221], v[214:215], v[220:221]
	v_pk_mul_f32 v[222:223], v[214:215], v[222:223]
	v_pk_mul_f32 v[216:217], v[56:57], v[216:217]
	v_pk_mul_f32 v[218:219], v[58:59], v[218:219]
	v_pk_mul_f32 v[220:221], v[60:61], v[220:221]
	v_pk_mul_f32 v[222:223], v[62:63], v[222:223]
	global_store_dwordx4 v3, v[216:219], s[18:19] offset:0
	global_store_dwordx4 v3, v[220:223], s[18:19] offset:16
	v_lshlrev_b32_e32 v224, 16, v196
	v_and_b32_e32 v225, 0xffff0000, v196
	v_lshlrev_b32_e32 v226, 16, v197
	v_and_b32_e32 v227, 0xffff0000, v197
	v_lshlrev_b32_e32 v228, 16, v198
	v_and_b32_e32 v229, 0xffff0000, v198
	v_lshlrev_b32_e32 v230, 16, v199
	v_and_b32_e32 v231, 0xffff0000, v199
	v_pk_mul_f32 v[224:225], v[214:215], v[224:225]
	v_pk_mul_f32 v[226:227], v[214:215], v[226:227]
	v_pk_mul_f32 v[228:229], v[214:215], v[228:229]
	v_pk_mul_f32 v[230:231], v[214:215], v[230:231]
	v_pk_mul_f32 v[224:225], v[64:65], v[224:225]
	v_pk_mul_f32 v[226:227], v[66:67], v[226:227]
	v_pk_mul_f32 v[228:229], v[68:69], v[228:229]
	v_pk_mul_f32 v[230:231], v[70:71], v[230:231]
	global_store_dwordx4 v3, v[224:227], s[18:19] offset:2048
	global_store_dwordx4 v3, v[228:231], s[18:19] offset:2064
	s_endpgm
